# v57 + FFN2 ctx split-K partial-slab stores written through (sc0 sc1) so their write-back overlaps the item instead of the phase barrier
# speedup vs baseline: 1.0062x; 1.0062x over previous
;     __device__ __forceinline__ void operator()(const f32x4 (&acc)[2][2][4][2], const Unit& u, int wr, int wc, int fr, int fq) const {
;         const int row0 = u.pm * BM + wr * 64 + fr; const int col0 = u.pn * BM + wc * 32 + 8 * fq;
;         if (u.nt != ntfull) {
;             const int seg = (u.kt0 == 0) ? 0 : (u.kt0 == 6 ? 1 : 2); const float nn = (seg == 1) ? (1.0f / 256.0f) : (1.0f / 384.0f);
;             const int crow0 = (u.pm == 32 ? 0 : 256) + wr * 64 + fr; const int slice = SEG ? seg : (u.kt0 >> 2);
; #pragma unroll
;             for (int ai = 0; ai < 2; ++ai)
; #pragma unroll
;                 for (int m = 0; m < 4; ++m) { const int row = row0 + ai * HALF + m * 16; float* yp = y32 + ((size_t)slice * 512 + crow0 + ai * HALF + m * 16) * DM + col0;
;                     float sc = 1.0f; if (SEG) sc = 1.0f / sqrtf(ss[(size_t)row * 4 + seg] * nn + LN_EPS);
; #pragma unroll
;                     for (int bj = 0; bj < 2; ++bj)
; #pragma unroll
;                         for (int n = 0; n < 2; ++n) *(f32x4*)(yp + bj * HALF + 4 * n) = acc[ai][bj][m][n] * sc; }
;             return;
.LBB0_1188:
	v_lshl_or_b32 v142, s52, 8, v145
	s_mov_b64 s[22:23], -1
	s_cmp_lg_u32 s48, 44
	v_ashrrev_i32_e32 v143, 31, v142
	s_cbranch_scc0 .LBB0_1191
	s_cmp_eq_u32 s47, 32
	s_cselect_b32 s15, 0, 0x100
	v_add_u32_e32 v148, s15, v17
	s_ashr_i32 s22, s16, 2
	s_ashr_i32 s23, s22, 31
	v_ashrrev_i32_e32 v149, 31, v148
	s_lshl_b64 s[22:23], s[22:23], 21
	v_lshlrev_b64 v[148:149], 12, v[148:149]
	v_lshl_add_u64 v[148:149], v[148:149], 0, s[22:23]
	v_or_b32_e32 v154, 0x10000, v148
	v_mov_b32_e32 v155, v149
	v_lshl_add_u64 v[150:151], s[10:11], 0, v[148:149]
	v_lshlrev_b64 v[152:153], 2, v[142:143]
	v_lshl_add_u64 v[154:155], s[10:11], 0, v[154:155]
	v_lshl_add_u64 v[150:151], v[150:151], 0, v[152:153]
	v_lshl_add_u64 v[154:155], v[154:155], 0, v[152:153]
	flat_store_dwordx4 v[150:151], v[130:133] sc0 sc1
	flat_store_dwordx4 v[150:151], v[126:129] offset:16 sc0 sc1
	flat_store_dwordx4 v[150:151], v[118:121] offset:512 sc0 sc1
	flat_store_dwordx4 v[150:151], v[110:113] offset:528 sc0 sc1
	flat_store_dwordx4 v[154:155], v[122:125] sc0 sc1
	flat_store_dwordx4 v[154:155], v[114:117] offset:16 sc0 sc1
	flat_store_dwordx4 v[154:155], v[102:105] offset:512 sc0 sc1
	flat_store_dwordx4 v[154:155], v[94:97] offset:528 sc0 sc1
	v_or_b32_e32 v154, 0x20000, v148
	v_mov_b32_e32 v155, v149
	v_or_b32_e32 v148, 0x30000, v148
	v_lshl_add_u64 v[154:155], s[10:11], 0, v[154:155]
	v_lshl_add_u64 v[148:149], s[10:11], 0, v[148:149]
	s_mov_b32 s15, 0x80000
	v_lshl_add_u64 v[154:155], v[154:155], 0, v[152:153]
	v_lshl_add_u64 v[148:149], v[148:149], 0, v[152:153]
	v_add_co_u32_e32 v152, vcc, s15, v150
	s_mov_b64 s[22:23], 0x80000
	s_nop 0
	v_addc_co_u32_e32 v153, vcc, 0, v151, vcc
	s_mov_b32 s15, 0x90000
	flat_store_dwordx4 v[154:155], v[106:109] sc0 sc1
	flat_store_dwordx4 v[154:155], v[98:101] offset:16 sc0 sc1
	flat_store_dwordx4 v[154:155], v[86:89] offset:512 sc0 sc1
	flat_store_dwordx4 v[154:155], v[78:81] offset:528 sc0 sc1
	flat_store_dwordx4 v[148:149], v[90:93] sc0 sc1
	flat_store_dwordx4 v[148:149], v[82:85] offset:16 sc0 sc1
	flat_store_dwordx4 v[148:149], v[74:77] offset:512 sc0 sc1
	flat_store_dwordx4 v[148:149], v[70:73] offset:528 sc0 sc1
	v_lshl_add_u64 v[148:149], v[150:151], 0, s[22:23]
	flat_store_dwordx4 v[152:153], v[66:69] sc0 sc1
	flat_store_dwordx4 v[148:149], v[62:65] offset:16 sc0 sc1
	flat_store_dwordx4 v[148:149], v[54:57] offset:512 sc0 sc1
	flat_store_dwordx4 v[148:149], v[46:49] offset:528 sc0 sc1
	v_add_co_u32_e32 v152, vcc, s15, v150
	s_mov_b64 s[22:23], 0x90000
	s_nop 0
	v_addc_co_u32_e32 v153, vcc, 0, v151, vcc
	v_lshl_add_u64 v[148:149], v[150:151], 0, s[22:23]
	flat_store_dwordx4 v[152:153], v[58:61] sc0 sc1
	flat_store_dwordx4 v[148:149], v[50:53] offset:16 sc0 sc1
	flat_store_dwordx4 v[148:149], v[38:41] offset:512 sc0 sc1
	flat_store_dwordx4 v[148:149], v[30:33] offset:528 sc0 sc1
	s_mov_b64 s[22:23], 0xa0000
	v_add_co_u32_e32 v152, vcc, 0xa0000, v150
	v_lshl_add_u64 v[148:149], v[150:151], 0, s[22:23]
	s_nop 0
	v_addc_co_u32_e32 v153, vcc, 0, v151, vcc
	s_mov_b64 s[22:23], 0xb0000
	flat_store_dwordx4 v[152:153], v[42:45] sc0 sc1
	flat_store_dwordx4 v[148:149], v[34:37] offset:16 sc0 sc1
	flat_store_dwordx4 v[148:149], v[22:25] offset:512 sc0 sc1
	flat_store_dwordx4 v[148:149], v[10:13] offset:528 sc0 sc1
	v_lshl_add_u64 v[148:149], v[150:151], 0, s[22:23]
	v_add_co_u32_e32 v150, vcc, 0xb0000, v150
	s_nop 1
	v_addc_co_u32_e32 v151, vcc, 0, v151, vcc
	flat_store_dwordx4 v[150:151], v[26:29] sc0 sc1
	flat_store_dwordx4 v[148:149], v[18:21] offset:16 sc0 sc1
	flat_store_dwordx4 v[148:149], v[6:9] offset:512 sc0 sc1
	flat_store_dwordx4 v[148:149], v[2:5] offset:528 sc0 sc1
	s_cbranch_execz .LBB0_1192
